# rstd-table loads only in GEMM phases whose epilogue uses them (MODE_IN / MODE_UP)
# speedup vs baseline: 1.0080x; 1.0027x over previous
; #define PG8_WAIT_V(n) asm volatile("s_waitcnt vmcnt(" #n ")" ::: "memory")
; #define PG8_BAR __builtin_amdgcn_s_barrier()
; #define PG8_STA(bufoff, gbase, ld) PG8_STAGE(bufoff, gbase, RA0 * (unsigned)(ld) + CC0, RA1 * (unsigned)(ld) + CC1)
; #define PG8_STB(bufoff, gbase, ld) PG8_STAGE(bufoff, gbase, RB0 * (unsigned)(ld) + CC0, RB1 * (unsigned)(ld) + CC1)
; __device__ __forceinline__ void epi_rstd(const float* ssq, int row0, int fq, float (&rs)[2][4]) {
;     float part[2][4][4];
; #pragma unroll
;     for (int ai = 0; ai < 2; ++ai)
; #pragma unroll
;         for (int m = 0; m < 4; ++m)
; #pragma unroll
;             for (int j = 0; j < 4; ++j) part[ai][m][j] = ssq[(size_t)(4 * fq + j) * M + row0 + ai * 128 + m * 16];
; #pragma unroll
;     for (int ai = 0; ai < 2; ++ai)
; #pragma unroll
;         for (int m = 0; m < 4; ++m) { float t = (part[ai][m][0] + part[ai][m][1]) + (part[ai][m][2] + part[ai][m][3]); t += __shfl_xor(t, 16); t += __shfl_xor(t, 32); rs[ai][m] = __builtin_amdgcn_rsqf(t * (1.0f / 1024.0f) + EPS); }
; __device__ __forceinline__ void gemm_phase(LAS unsigned char* lds, const Sched& S, const Epi& E) {
;     ...
;     int lda = cur.lda, ldb = cur.ldb;
;     { const size_t hA = (size_t)HALF * lda * 2, hB = (size_t)HALF * ldb * 2;
;     PG8_STB(PG8_SB(0, 0), cB, ldb); PG8_STB(PG8_SB(0, 1), cB + hB, ldb); PG8_STA(PG8_SA(0, 0), cA, lda); PG8_STA(PG8_SA(0, 1), cA + hA, lda);
;     if (wr == 1) PG8_BAR;
;     PG8_WAIT_V(2); PG8_BAR;
;     PG8_STB(PG8_SB(1, 0), cB + kstep, ldb); PG8_STA(PG8_SA(1, 0), cA + kstep, lda); PG8_STB(PG8_SB(1, 1), cB + hB + kstep, ldb);
;     PG8_WAIT_V(6); PG8_BAR; }
;     for (;;) {
.LBB0_256:
	v_readlane_b32 s12, v250, 13
	s_mov_b32 s13, -1
	s_cmp_eq_u32 s12, 0
	s_cbranch_scc1 .Lmy_tab_yes
	s_cmp_eq_u32 s12, 5
	s_cbranch_scc1 .Lmy_tab_yes
	v_writelane_b32 v250, s13, 41
	s_branch .Lmy_tab_done
.Lmy_tab_yes:
	v_writelane_b32 v250, s95, 41
	v_readlane_b32 s12, v250, 3
	v_readlane_b32 s13, v250, 4
	v_and_b32_e32 v64, 0xff, v195
	v_lshl_add_u32 v64, s95, 8, v64
	v_lshlrev_b32_e32 v64, 2, v64
	s_nop 3
	global_load_dword v66, v64, s[12:13]
	v_add_u32_e32 v65, 0x10000, v64
	global_load_dword v67, v65, s[12:13]
	v_add_u32_e32 v65, 0x20000, v64
	global_load_dword v68, v65, s[12:13]
	v_add_u32_e32 v65, 0x30000, v64
	global_load_dword v69, v65, s[12:13]
	v_add_u32_e32 v65, 0x40000, v64
	global_load_dword v70, v65, s[12:13]
	v_add_u32_e32 v65, 0x50000, v64
	global_load_dword v71, v65, s[12:13]
	v_add_u32_e32 v65, 0x60000, v64
	global_load_dword v72, v65, s[12:13]
	v_add_u32_e32 v65, 0x70000, v64
	global_load_dword v73, v65, s[12:13]
	v_add_u32_e32 v65, 0x80000, v64
	global_load_dword v74, v65, s[12:13]
	v_add_u32_e32 v65, 0x90000, v64
	global_load_dword v75, v65, s[12:13]
	v_add_u32_e32 v65, 0xa0000, v64
	global_load_dword v76, v65, s[12:13]
	v_add_u32_e32 v65, 0xb0000, v64
	global_load_dword v77, v65, s[12:13]
	v_add_u32_e32 v65, 0xc0000, v64
	global_load_dword v78, v65, s[12:13]
	v_add_u32_e32 v65, 0xd0000, v64
	global_load_dword v79, v65, s[12:13]
	v_add_u32_e32 v65, 0xe0000, v64
	global_load_dword v80, v65, s[12:13]
	v_add_u32_e32 v65, 0xf0000, v64
	global_load_dword v81, v65, s[12:13]
.Lmy_tab_done:
	v_bfe_u32 v19, v17, 4, 2
	v_and_b32_e32 v18, 15, v17
	v_lshlrev_b32_e32 v21, 4, v19
	v_lshlrev_b32_e32 v17, 2, v17
	s_and_b32 s11, s7, 3
	v_lshl_or_b32 v239, s6, 6, v18
	v_lshl_or_b32 v18, v18, 6, v21
	s_lshl_b32 s6, s6, 13
	v_and_b32_e32 v17, 32, v17
	v_bitop3_b32 v240, v18, s6, v17 bitop3:0xde
	s_lshl_b32 s6, s11, 12
	v_bitop3_b32 v241, v18, s6, v17 bitop3:0xde
	v_readlane_b32 s6, v250, 7
	v_readlane_b32 s7, v250, 8
	s_lshl_b64 s[6:7], s[6:7], 2
	s_waitcnt lgkmcnt(0)
	s_add_u32 s4, s4, s6
	s_addc_u32 s5, s5, s7
	s_add_u32 s62, s70, 0x800000
	s_addc_u32 s63, s71, 0
	v_lshl_add_u64 v[2:3], v[2:3], 0, s[52:53]
	s_add_i32 m0, s34, 0x18000
	v_readlane_b32 s12, v250, 41
	s_nop 0
	s_cmp_eq_u32 s12, -1
	s_cbranch_scc1 .Lmy_w2
	s_waitcnt vmcnt(18)
	s_branch .Lmy_wdone
.Lmy_w2:
	s_waitcnt vmcnt(2)
.Lmy_wdone:
	s_barrier
	global_load_lds_dwordx4 v[2:3], off
	v_lshl_add_u64 v[2:3], v[4:5], 0, s[52:53]
	s_add_i32 m0, s34, 0x1a000
	s_add_i32 s90, s34, 0x8000
	global_load_lds_dwordx4 v[2:3], off
	v_lshl_add_u64 v[2:3], v[10:11], 0, s[52:53]
	s_mov_b32 m0, s90
	s_add_i32 s73, s34, 0xa000
	global_load_lds_dwordx4 v[2:3], off
	v_lshl_add_u64 v[2:3], v[12:13], 0, s[52:53]
	s_mov_b32 m0, s73
	v_writelane_b32 v250, s4, 27
	global_load_lds_dwordx4 v[2:3], off
	v_lshl_add_u64 v[2:3], v[6:7], 0, s[52:53]
	s_add_i32 m0, s34, 0x1c000
	v_writelane_b32 v250, s5, 28
	global_load_lds_dwordx4 v[2:3], off
	v_lshl_add_u64 v[2:3], v[8:9], 0, s[52:53]
	s_add_i32 m0, s34, 0x1e000
	s_cmpk_lt_u32 s2, 0x100
	global_load_lds_dwordx4 v[2:3], off
	s_cselect_b64 s[4:5], -1, 0
	s_lshl_b32 s6, s11, 14
	v_writelane_b32 v250, s11, 29
	s_or_b32 s6, s6, 0xfff80000
	v_writelane_b32 v250, s6, 30
	s_lshl_b32 s82, s15, 3
	v_readlane_b32 s6, v250, 21
	v_readlane_b32 s7, v250, 22
	v_readlane_b32 s61, v250, 20
	s_waitcnt vmcnt(6)
	v_readlane_b32 s12, v250, 41
	s_nop 0
	s_cmp_eq_u32 s12, -1
	s_cbranch_scc1 .Lmy_red_skip
	v_add_f32_e32 v66, v66, v67
	v_add_f32_e32 v68, v68, v69
	v_add_f32_e32 v66, v66, v68
	v_add_f32_e32 v70, v70, v71
	v_add_f32_e32 v72, v72, v73
	v_add_f32_e32 v70, v70, v72
	v_add_f32_e32 v74, v74, v75
	v_add_f32_e32 v76, v76, v77
	v_add_f32_e32 v74, v74, v76
	v_add_f32_e32 v78, v78, v79
	v_add_f32_e32 v80, v80, v81
	v_add_f32_e32 v78, v78, v80
	v_add_f32_e32 v66, v66, v70
	v_add_f32_e32 v74, v74, v78
	v_add_f32_e32 v66, v66, v74
	v_fmamk_f32 v66, v66, 0x3a800000, v197
	v_rsq_f32_e32 v66, v66
	v_and_b32_e32 v65, 0xff, v195
	v_lshlrev_b32_e32 v65, 2, v65
	v_add_u32_e32 v65, 0x20800, v65
	ds_write_b32 v65, v66
	v_writelane_b32 v250, s95, 41
.Lmy_red_skip:
	v_and_b32_e32 v0, 1, v0
	v_cndmask_b32_e64 v2, 0, 1, s[6:7]
	s_lshr_b32 s6, s61, 6
	v_readfirstlane_b32 s36, v2
	v_cvt_f32_u32_e32 v2, s82
	v_writelane_b32 v250, s6, 31
	s_sub_i32 s6, 0, s82
	v_lshlrev_b32_e32 v20, 3, v19
	v_rcp_iflag_f32_e32 v2, v2
	v_lshlrev_b32_e32 v198, 16, v19
	v_lshl_or_b32 v242, s11, 5, v20
	s_mov_b32 s2, 0
	v_mul_f32_e32 v2, 0x4f7ffffe, v2
	v_cvt_u32_f32_e32 v2, v2
	v_cmp_eq_u32_e64 s[40:41], 0, v19
	v_or_b32_e32 v200, 0x4000, v198
	v_or_b32_e32 v202, 0x8000, v198
	v_readfirstlane_b32 s7, v2
	s_mul_i32 s6, s6, s7
	s_mul_hi_u32 s6, s7, s6
	s_add_i32 s6, s7, s6
	v_writelane_b32 v250, s6, 32
	v_lshlrev_b32_e32 v2, 1, v14
	v_lshl_add_u32 v206, v0, 6, v2
	v_and_b32_e32 v0, 1, v15
	v_lshlrev_b32_e32 v2, 1, v16
	v_readlane_b32 s6, v250, 12
	v_or_b32_e32 v204, 0xc000, v198
	s_mov_b32 s17, s31
	v_lshl_add_u32 v208, v0, 6, v2
	v_readlane_b32 s83, v250, 13
	s_mov_b32 s20, s6
	s_mov_b32 s11, s61
	s_mov_b64 s[12:13], s[8:9]
	s_mov_b64 s[6:7], s[96:97]
	s_waitcnt lgkmcnt(0)
	s_barrier
	s_branch .LBB0_259
